# v65 + gate epilogue re-emitted with the second half reusing the first half's 1/rms values and a bias prefetched in the first half (no load / LDS wait behind the first half's stores)
# speedup vs baseline: 1.0064x; 1.0064x over previous
; __device__ __forceinline__ u32x4 pack8(const float (&v)[8]) { u32x4 w; w.x = pk2(v[0], v[1]); w.y = pk2(v[2], v[3]); w.z = pk2(v[4], v[5]); w.w = pk2(v[6], v[7]); return w; }
;     __device__ __forceinline__ bool operator()(Acc& acc, const Unit& u, int wr, int wc, int fr, int fq, const LAS float* rstab) const {
;     ...
;         for (int bj = 0; bj < 2; ++bj) {
;             const int colt = u.pn * BM + bj * HALF;
;             if (colt >= C_G) {
;                 const int pl = (u.pn < 19) ? bj : 2, go = (u.pn < 19) ? (u.pn - 11) * HALF : colt - (C_G + 2048);
;                 bf16_t* p0 = Gt + (size_t)rowb * 3072 + pl * 1024 + go + cl;
;                 float bg[8];
;                 { const f32x4 b0 = gld<f32x4>(bgate + pl * 1024 + go + cl), b1 = gld<f32x4>(bgate + pl * 1024 + go + cl + 4);
; #pragma unroll
;                   for (int e = 0; e < 4; ++e) { bg[e] = -LOG2E * b0[e]; bg[4 + e] = -LOG2E * b1[e]; } }
; #pragma unroll
;                 for (int ai = 0; ai < 2; ++ai)
; #pragma unroll
;                     for (int m = 0; m < 4; ++m) {
;                         const float nrs = -LOG2E * rsp[ai * HALF + m * 16];
;                         float v[8];
; #pragma unroll
;                         for (int e = 0; e < 4; ++e) {
;                             v[e] = 1.0f + __builtin_amdgcn_exp2f(fminf(__builtin_fmaf(acc[ai][bj][m][0][e], nrs, bg[e]), 86.f));
;                             v[4 + e] = 1.0f + __builtin_amdgcn_exp2f(fminf(__builtin_fmaf(acc[ai][bj][m][1][e], nrs, bg[4 + e]), 86.f));
;                         }
;                         gst<u32x4>(p0 + (ai * HALF + m * 16) * 3072, pack8(v));
;                         asm volatile("" ::: "memory");
;                     }
.LBB0_422:
	s_movk_i32 s9, 0x1800
	s_and_b64 vcc, exec, s[14:15]
	v_readlane_b32 s14, v254, 57
	s_lshl_b32 s60, s70, 7
	v_mad_i64_i32 v[132:133], s[16:17], v2, s9, 0
	v_readlane_b32 s15, v254, 58
	s_addk_i32 s60, 0xfa80
	v_lshlrev_b32_e32 v159, 2, v155
	v_lshl_add_u64 v[140:141], s[14:15], 0, v[132:133]
	s_cbranch_vccz .LBB0_432
	s_add_i32 s9, s8, 0xffffed00
	s_and_b64 s[14:15], s[10:11], exec
	s_cselect_b32 s14, s60, s9
	s_cselect_b32 s9, 0, 0x800
	s_lshl_b32 s26, s9, 1
	s_ashr_i32 s15, s14, 31
	s_lshl_b32 s9, s9, 2
	v_lshl_add_u64 v[132:133], v[140:141], 0, s[26:27]
	s_add_u32 s9, s62, s9
	v_lshl_add_u64 v[142:143], s[14:15], 1, v[132:133]
	s_addc_u32 s16, s63, 0
	s_lshl_b64 s[14:15], s[14:15], 2
	s_add_u32 s14, s9, s14
	s_addc_u32 s15, s16, s15
	v_lshlrev_b32_e32 v0, 1, v155
	v_lshl_add_u64 v[142:143], v[142:143], 0, v[0:1]
	global_load_dwordx4 v[180:183], v159, s[14:15] offset:16
	global_load_dwordx4 v[176:179], v159, s[14:15]
	s_and_b64 s[100:101], s[10:11], exec
	s_mov_b32 s101, 0x200
	s_cselect_b32 s100, 0x1000, s101
	s_add_u32 s100, s14, s100
	s_addc_u32 s101, s15, 0
	global_load_dwordx4 v[220:223], v159, s[100:101] offset:16
	global_load_dwordx4 v[216:219], v159, s[100:101]
	ds_read_b32 v184, v154
	ds_read_b32 v185, v154 offset:64
	ds_read_b32 v186, v154 offset:128
	ds_read_b32 v187, v154 offset:192
	ds_read_b32 v188, v154 offset:512
	ds_read_b32 v189, v154 offset:576
	ds_read_b32 v190, v154 offset:640
	ds_read_b32 v191, v154 offset:704
	v_mov_b32_e32 v192, 0xbfb8aa3b
	s_waitcnt vmcnt(0)
	v_pk_mul_f32 v[176:177], v[176:177], v[192:193] op_sel_hi:[1,0]
	v_pk_mul_f32 v[178:179], v[178:179], v[192:193] op_sel_hi:[1,0]
	v_pk_mul_f32 v[180:181], v[180:181], v[192:193] op_sel_hi:[1,0]
	v_pk_mul_f32 v[182:183], v[182:183], v[192:193] op_sel_hi:[1,0]
	v_pk_mul_f32 v[216:217], v[216:217], v[192:193] op_sel_hi:[1,0]
	v_pk_mul_f32 v[218:219], v[218:219], v[192:193] op_sel_hi:[1,0]
	v_pk_mul_f32 v[220:221], v[220:221], v[192:193] op_sel_hi:[1,0]
	v_pk_mul_f32 v[222:223], v[222:223], v[192:193] op_sel_hi:[1,0]
	s_waitcnt lgkmcnt(0)
	v_mul_f32_e32 v184, 0xbfb8aa3b, v184
	v_mul_f32_e32 v185, 0xbfb8aa3b, v185
	v_mul_f32_e32 v186, 0xbfb8aa3b, v186
	v_mul_f32_e32 v187, 0xbfb8aa3b, v187
	v_mul_f32_e32 v188, 0xbfb8aa3b, v188
	v_mul_f32_e32 v189, 0xbfb8aa3b, v189
	v_mul_f32_e32 v190, 0xbfb8aa3b, v190
	v_mul_f32_e32 v191, 0xbfb8aa3b, v191
	v_pk_fma_f32 v[208:209], v[120:121], v[184:185], v[176:177] op_sel_hi:[1,0,1]
	v_pk_fma_f32 v[210:211], v[122:123], v[184:185], v[178:179] op_sel_hi:[1,0,1]
	v_pk_fma_f32 v[212:213], v[112:113], v[184:185], v[180:181] op_sel_hi:[1,0,1]
	v_pk_fma_f32 v[214:215], v[114:115], v[184:185], v[182:183] op_sel_hi:[1,0,1]
	v_min_f32_e32 v208, 0x42ac0000, v208
	v_min_f32_e32 v209, 0x42ac0000, v209
	v_min_f32_e32 v210, 0x42ac0000, v210
	v_min_f32_e32 v211, 0x42ac0000, v211
	v_min_f32_e32 v212, 0x42ac0000, v212
	v_min_f32_e32 v213, 0x42ac0000, v213
	v_min_f32_e32 v214, 0x42ac0000, v214
	v_min_f32_e32 v215, 0x42ac0000, v215
	v_exp_f32_e32 v208, v208
	v_exp_f32_e32 v209, v209
	v_exp_f32_e32 v210, v210
	v_exp_f32_e32 v211, v211
	v_exp_f32_e32 v212, v212
	v_exp_f32_e32 v213, v213
	v_exp_f32_e32 v214, v214
	v_exp_f32_e32 v215, v215
	v_pk_add_f32 v[208:209], v[208:209], 1.0 op_sel_hi:[1,0]
	v_pk_add_f32 v[210:211], v[210:211], 1.0 op_sel_hi:[1,0]
	v_pk_add_f32 v[212:213], v[212:213], 1.0 op_sel_hi:[1,0]
	v_pk_add_f32 v[214:215], v[214:215], 1.0 op_sel_hi:[1,0]
	v_cvt_pk_bf16_f32 v132, v208, v209
	v_cvt_pk_bf16_f32 v133, v210, v211
	v_cvt_pk_bf16_f32 v134, v212, v213
	v_cvt_pk_bf16_f32 v135, v214, v215
	global_store_dwordx4 v[142:143], v[132:135], off
	v_pk_fma_f32 v[208:209], v[100:101], v[184:185], v[176:177] op_sel:[0,1,0] op_sel_hi:[1,1,1]
	v_pk_fma_f32 v[210:211], v[102:103], v[184:185], v[178:179] op_sel:[0,1,0] op_sel_hi:[1,1,1]
	v_pk_fma_f32 v[212:213], v[88:89], v[184:185], v[180:181] op_sel:[0,1,0] op_sel_hi:[1,1,1]
	v_pk_fma_f32 v[214:215], v[90:91], v[184:185], v[182:183] op_sel:[0,1,0] op_sel_hi:[1,1,1]
	v_min_f32_e32 v208, 0x42ac0000, v208
	v_min_f32_e32 v209, 0x42ac0000, v209
	v_min_f32_e32 v210, 0x42ac0000, v210
	v_min_f32_e32 v211, 0x42ac0000, v211
	v_min_f32_e32 v212, 0x42ac0000, v212
	v_min_f32_e32 v213, 0x42ac0000, v213
	v_min_f32_e32 v214, 0x42ac0000, v214
	v_min_f32_e32 v215, 0x42ac0000, v215
	v_exp_f32_e32 v208, v208
	v_exp_f32_e32 v209, v209
	v_exp_f32_e32 v210, v210
	v_exp_f32_e32 v211, v211
	v_exp_f32_e32 v212, v212
	v_exp_f32_e32 v213, v213
	v_exp_f32_e32 v214, v214
	v_exp_f32_e32 v215, v215
	v_pk_add_f32 v[208:209], v[208:209], 1.0 op_sel_hi:[1,0]
	v_pk_add_f32 v[210:211], v[210:211], 1.0 op_sel_hi:[1,0]
	v_pk_add_f32 v[212:213], v[212:213], 1.0 op_sel_hi:[1,0]
	v_pk_add_f32 v[214:215], v[214:215], 1.0 op_sel_hi:[1,0]
	v_cvt_pk_bf16_f32 v132, v208, v209
	v_cvt_pk_bf16_f32 v133, v210, v211
	v_cvt_pk_bf16_f32 v134, v212, v213
	v_cvt_pk_bf16_f32 v135, v214, v215
	v_add_co_u32_e32 v194, vcc, 0x18000, v142
	v_addc_co_u32_e32 v195, vcc, 0, v143, vcc
	global_store_dwordx4 v[194:195], v[132:135], off
	v_pk_fma_f32 v[208:209], v[68:69], v[186:187], v[176:177] op_sel_hi:[1,0,1]
	v_pk_fma_f32 v[210:211], v[70:71], v[186:187], v[178:179] op_sel_hi:[1,0,1]
	v_pk_fma_f32 v[212:213], v[56:57], v[186:187], v[180:181] op_sel_hi:[1,0,1]
	v_pk_fma_f32 v[214:215], v[58:59], v[186:187], v[182:183] op_sel_hi:[1,0,1]
	v_min_f32_e32 v208, 0x42ac0000, v208
	v_min_f32_e32 v209, 0x42ac0000, v209
	v_min_f32_e32 v210, 0x42ac0000, v210
	v_min_f32_e32 v211, 0x42ac0000, v211
	v_min_f32_e32 v212, 0x42ac0000, v212
	v_min_f32_e32 v213, 0x42ac0000, v213
	v_min_f32_e32 v214, 0x42ac0000, v214
	v_min_f32_e32 v215, 0x42ac0000, v215
; __device__ __forceinline__ u32x4 pack8(const float (&v)[8]) { u32x4 w; w.x = pk2(v[0], v[1]); w.y = pk2(v[2], v[3]); w.z = pk2(v[4], v[5]); w.w = pk2(v[6], v[7]); return w; }
;     __device__ __forceinline__ bool operator()(Acc& acc, const Unit& u, int wr, int wc, int fr, int fq, const LAS float* rstab) const {
;     ...
; #pragma unroll
;                 for (int ai = 0; ai < 2; ++ai)
; #pragma unroll
;                     for (int m = 0; m < 4; ++m) {
;                         const float nrs = -LOG2E * rsp[ai * HALF + m * 16];
;                         float v[8];
; #pragma unroll
;                         for (int e = 0; e < 4; ++e) {
;                             v[e] = 1.0f + __builtin_amdgcn_exp2f(fminf(__builtin_fmaf(acc[ai][bj][m][0][e], nrs, bg[e]), 86.f));
;                             v[4 + e] = 1.0f + __builtin_amdgcn_exp2f(fminf(__builtin_fmaf(acc[ai][bj][m][1][e], nrs, bg[4 + e]), 86.f));
;                         }
;                         gst<u32x4>(p0 + (ai * HALF + m * 16) * 3072, pack8(v));
;                         asm volatile("" ::: "memory");
;                     }
	v_exp_f32_e32 v208, v208
	v_exp_f32_e32 v209, v209
	v_exp_f32_e32 v210, v210
	v_exp_f32_e32 v211, v211
	v_exp_f32_e32 v212, v212
	v_exp_f32_e32 v213, v213
	v_exp_f32_e32 v214, v214
	v_exp_f32_e32 v215, v215
	v_pk_add_f32 v[208:209], v[208:209], 1.0 op_sel_hi:[1,0]
	v_pk_add_f32 v[210:211], v[210:211], 1.0 op_sel_hi:[1,0]
	v_pk_add_f32 v[212:213], v[212:213], 1.0 op_sel_hi:[1,0]
	v_pk_add_f32 v[214:215], v[214:215], 1.0 op_sel_hi:[1,0]
	v_cvt_pk_bf16_f32 v132, v208, v209
	v_cvt_pk_bf16_f32 v133, v210, v211
	v_cvt_pk_bf16_f32 v134, v212, v213
	v_cvt_pk_bf16_f32 v135, v214, v215
	v_add_co_u32_e32 v194, vcc, 0x30000, v142
	v_addc_co_u32_e32 v195, vcc, 0, v143, vcc
	global_store_dwordx4 v[194:195], v[132:135], off
	v_pk_fma_f32 v[208:209], v[36:37], v[186:187], v[176:177] op_sel:[0,1,0] op_sel_hi:[1,1,1]
	v_pk_fma_f32 v[210:211], v[38:39], v[186:187], v[178:179] op_sel:[0,1,0] op_sel_hi:[1,1,1]
	v_pk_fma_f32 v[212:213], v[28:29], v[186:187], v[180:181] op_sel:[0,1,0] op_sel_hi:[1,1,1]
	v_pk_fma_f32 v[214:215], v[30:31], v[186:187], v[182:183] op_sel:[0,1,0] op_sel_hi:[1,1,1]
	v_min_f32_e32 v208, 0x42ac0000, v208
	v_min_f32_e32 v209, 0x42ac0000, v209
	v_min_f32_e32 v210, 0x42ac0000, v210
	v_min_f32_e32 v211, 0x42ac0000, v211
	v_min_f32_e32 v212, 0x42ac0000, v212
	v_min_f32_e32 v213, 0x42ac0000, v213
	v_min_f32_e32 v214, 0x42ac0000, v214
	v_min_f32_e32 v215, 0x42ac0000, v215
	v_exp_f32_e32 v208, v208
	v_exp_f32_e32 v209, v209
	v_exp_f32_e32 v210, v210
	v_exp_f32_e32 v211, v211
	v_exp_f32_e32 v212, v212
	v_exp_f32_e32 v213, v213
	v_exp_f32_e32 v214, v214
	v_exp_f32_e32 v215, v215
	v_pk_add_f32 v[208:209], v[208:209], 1.0 op_sel_hi:[1,0]
	v_pk_add_f32 v[210:211], v[210:211], 1.0 op_sel_hi:[1,0]
	v_pk_add_f32 v[212:213], v[212:213], 1.0 op_sel_hi:[1,0]
	v_pk_add_f32 v[214:215], v[214:215], 1.0 op_sel_hi:[1,0]
	v_cvt_pk_bf16_f32 v132, v208, v209
	v_cvt_pk_bf16_f32 v133, v210, v211
	v_cvt_pk_bf16_f32 v134, v212, v213
	v_cvt_pk_bf16_f32 v135, v214, v215
	v_add_co_u32_e32 v194, vcc, 0x48000, v142
	v_addc_co_u32_e32 v195, vcc, 0, v143, vcc
	global_store_dwordx4 v[194:195], v[132:135], off
	v_pk_fma_f32 v[208:209], v[72:73], v[188:189], v[176:177] op_sel_hi:[1,0,1]
	v_pk_fma_f32 v[210:211], v[74:75], v[188:189], v[178:179] op_sel_hi:[1,0,1]
	v_pk_fma_f32 v[212:213], v[60:61], v[188:189], v[180:181] op_sel_hi:[1,0,1]
	v_pk_fma_f32 v[214:215], v[62:63], v[188:189], v[182:183] op_sel_hi:[1,0,1]
	v_min_f32_e32 v208, 0x42ac0000, v208
	v_min_f32_e32 v209, 0x42ac0000, v209
	v_min_f32_e32 v210, 0x42ac0000, v210
	v_min_f32_e32 v211, 0x42ac0000, v211
	v_min_f32_e32 v212, 0x42ac0000, v212
	v_min_f32_e32 v213, 0x42ac0000, v213
	v_min_f32_e32 v214, 0x42ac0000, v214
	v_min_f32_e32 v215, 0x42ac0000, v215
	v_exp_f32_e32 v208, v208
	v_exp_f32_e32 v209, v209
	v_exp_f32_e32 v210, v210
	v_exp_f32_e32 v211, v211
	v_exp_f32_e32 v212, v212
	v_exp_f32_e32 v213, v213
	v_exp_f32_e32 v214, v214
	v_exp_f32_e32 v215, v215
	v_pk_add_f32 v[208:209], v[208:209], 1.0 op_sel_hi:[1,0]
	v_pk_add_f32 v[210:211], v[210:211], 1.0 op_sel_hi:[1,0]
	v_pk_add_f32 v[212:213], v[212:213], 1.0 op_sel_hi:[1,0]
	v_pk_add_f32 v[214:215], v[214:215], 1.0 op_sel_hi:[1,0]
	v_cvt_pk_bf16_f32 v132, v208, v209
	v_cvt_pk_bf16_f32 v133, v210, v211
	v_cvt_pk_bf16_f32 v134, v212, v213
	v_cvt_pk_bf16_f32 v135, v214, v215
	v_add_co_u32_e32 v194, vcc, 0xc0000, v142
	v_addc_co_u32_e32 v195, vcc, 0, v143, vcc
	global_store_dwordx4 v[194:195], v[132:135], off
	v_pk_fma_f32 v[208:209], v[40:41], v[188:189], v[176:177] op_sel:[0,1,0] op_sel_hi:[1,1,1]
	v_pk_fma_f32 v[210:211], v[42:43], v[188:189], v[178:179] op_sel:[0,1,0] op_sel_hi:[1,1,1]
	v_pk_fma_f32 v[212:213], v[32:33], v[188:189], v[180:181] op_sel:[0,1,0] op_sel_hi:[1,1,1]
	v_pk_fma_f32 v[214:215], v[34:35], v[188:189], v[182:183] op_sel:[0,1,0] op_sel_hi:[1,1,1]
	v_min_f32_e32 v208, 0x42ac0000, v208
	v_min_f32_e32 v209, 0x42ac0000, v209
	v_min_f32_e32 v210, 0x42ac0000, v210
	v_min_f32_e32 v211, 0x42ac0000, v211
	v_min_f32_e32 v212, 0x42ac0000, v212
	v_min_f32_e32 v213, 0x42ac0000, v213
	v_min_f32_e32 v214, 0x42ac0000, v214
	v_min_f32_e32 v215, 0x42ac0000, v215
	v_exp_f32_e32 v208, v208
	v_exp_f32_e32 v209, v209
	v_exp_f32_e32 v210, v210
	v_exp_f32_e32 v211, v211
	v_exp_f32_e32 v212, v212
	v_exp_f32_e32 v213, v213
	v_exp_f32_e32 v214, v214
	v_exp_f32_e32 v215, v215
	v_pk_add_f32 v[208:209], v[208:209], 1.0 op_sel_hi:[1,0]
	v_pk_add_f32 v[210:211], v[210:211], 1.0 op_sel_hi:[1,0]
	v_pk_add_f32 v[212:213], v[212:213], 1.0 op_sel_hi:[1,0]
	v_pk_add_f32 v[214:215], v[214:215], 1.0 op_sel_hi:[1,0]
	v_cvt_pk_bf16_f32 v132, v208, v209
	v_cvt_pk_bf16_f32 v133, v210, v211
	v_cvt_pk_bf16_f32 v134, v212, v213
	v_cvt_pk_bf16_f32 v135, v214, v215
	v_add_co_u32_e32 v194, vcc, 0xd8000, v142
	v_addc_co_u32_e32 v195, vcc, 0, v143, vcc
	global_store_dwordx4 v[194:195], v[132:135], off
	v_pk_fma_f32 v[208:209], v[16:17], v[190:191], v[176:177] op_sel_hi:[1,0,1]
	v_pk_fma_f32 v[210:211], v[18:19], v[190:191], v[178:179] op_sel_hi:[1,0,1]
	v_pk_fma_f32 v[212:213], v[12:13], v[190:191], v[180:181] op_sel_hi:[1,0,1]
	v_pk_fma_f32 v[214:215], v[14:15], v[190:191], v[182:183] op_sel_hi:[1,0,1]
	v_min_f32_e32 v208, 0x42ac0000, v208
	v_min_f32_e32 v209, 0x42ac0000, v209
	v_min_f32_e32 v210, 0x42ac0000, v210
	v_min_f32_e32 v211, 0x42ac0000, v211
	v_min_f32_e32 v212, 0x42ac0000, v212
	v_min_f32_e32 v213, 0x42ac0000, v213
	v_min_f32_e32 v214, 0x42ac0000, v214
	v_min_f32_e32 v215, 0x42ac0000, v215
	v_exp_f32_e32 v208, v208
	v_exp_f32_e32 v209, v209
	v_exp_f32_e32 v210, v210
	v_exp_f32_e32 v211, v211
	v_exp_f32_e32 v212, v212
	v_exp_f32_e32 v213, v213
	v_exp_f32_e32 v214, v214
; __device__ __forceinline__ u32x4 pack8(const float (&v)[8]) { u32x4 w; w.x = pk2(v[0], v[1]); w.y = pk2(v[2], v[3]); w.z = pk2(v[4], v[5]); w.w = pk2(v[6], v[7]); return w; }
;     __device__ __forceinline__ bool operator()(Acc& acc, const Unit& u, int wr, int wc, int fr, int fq, const LAS float* rstab) const {
;     ...
;         for (int bj = 0; bj < 2; ++bj) {
;             const int colt = u.pn * BM + bj * HALF;
;             if (colt >= C_G) {
;                 const int pl = (u.pn < 19) ? bj : 2, go = (u.pn < 19) ? (u.pn - 11) * HALF : colt - (C_G + 2048);
;                 bf16_t* p0 = Gt + (size_t)rowb * 3072 + pl * 1024 + go + cl;
;                 float bg[8];
;                 { const f32x4 b0 = gld<f32x4>(bgate + pl * 1024 + go + cl), b1 = gld<f32x4>(bgate + pl * 1024 + go + cl + 4);
; #pragma unroll
;                   for (int e = 0; e < 4; ++e) { bg[e] = -LOG2E * b0[e]; bg[4 + e] = -LOG2E * b1[e]; } }
; #pragma unroll
;                 for (int ai = 0; ai < 2; ++ai)
; #pragma unroll
;                     for (int m = 0; m < 4; ++m) {
;                         const float nrs = -LOG2E * rsp[ai * HALF + m * 16];
;                         float v[8];
; #pragma unroll
;                         for (int e = 0; e < 4; ++e) {
;                             v[e] = 1.0f + __builtin_amdgcn_exp2f(fminf(__builtin_fmaf(acc[ai][bj][m][0][e], nrs, bg[e]), 86.f));
;                             v[4 + e] = 1.0f + __builtin_amdgcn_exp2f(fminf(__builtin_fmaf(acc[ai][bj][m][1][e], nrs, bg[4 + e]), 86.f));
;                         }
;                         gst<u32x4>(p0 + (ai * HALF + m * 16) * 3072, pack8(v));
;                         asm volatile("" ::: "memory");
;                     }
	v_exp_f32_e32 v215, v215
	v_pk_add_f32 v[208:209], v[208:209], 1.0 op_sel_hi:[1,0]
	v_pk_add_f32 v[210:211], v[210:211], 1.0 op_sel_hi:[1,0]
	v_pk_add_f32 v[212:213], v[212:213], 1.0 op_sel_hi:[1,0]
	v_pk_add_f32 v[214:215], v[214:215], 1.0 op_sel_hi:[1,0]
	v_cvt_pk_bf16_f32 v132, v208, v209
	v_cvt_pk_bf16_f32 v133, v210, v211
	v_cvt_pk_bf16_f32 v134, v212, v213
	v_cvt_pk_bf16_f32 v135, v214, v215
	v_add_co_u32_e32 v194, vcc, 0xf0000, v142
	v_addc_co_u32_e32 v195, vcc, 0, v143, vcc
	global_store_dwordx4 v[194:195], v[132:135], off
	v_pk_fma_f32 v[208:209], v[8:9], v[190:191], v[176:177] op_sel:[0,1,0] op_sel_hi:[1,1,1]
	v_pk_fma_f32 v[210:211], v[10:11], v[190:191], v[178:179] op_sel:[0,1,0] op_sel_hi:[1,1,1]
	v_pk_fma_f32 v[212:213], v[4:5], v[190:191], v[180:181] op_sel:[0,1,0] op_sel_hi:[1,1,1]
	v_pk_fma_f32 v[214:215], v[6:7], v[190:191], v[182:183] op_sel:[0,1,0] op_sel_hi:[1,1,1]
	v_min_f32_e32 v208, 0x42ac0000, v208
	v_min_f32_e32 v209, 0x42ac0000, v209
	v_min_f32_e32 v210, 0x42ac0000, v210
	v_min_f32_e32 v211, 0x42ac0000, v211
	v_min_f32_e32 v212, 0x42ac0000, v212
	v_min_f32_e32 v213, 0x42ac0000, v213
	v_min_f32_e32 v214, 0x42ac0000, v214
	v_min_f32_e32 v215, 0x42ac0000, v215
	v_exp_f32_e32 v208, v208
	v_exp_f32_e32 v209, v209
	v_exp_f32_e32 v210, v210
	v_exp_f32_e32 v211, v211
	v_exp_f32_e32 v212, v212
	v_exp_f32_e32 v213, v213
	v_exp_f32_e32 v214, v214
	v_exp_f32_e32 v215, v215
	v_pk_add_f32 v[208:209], v[208:209], 1.0 op_sel_hi:[1,0]
	v_pk_add_f32 v[210:211], v[210:211], 1.0 op_sel_hi:[1,0]
	v_pk_add_f32 v[212:213], v[212:213], 1.0 op_sel_hi:[1,0]
	v_pk_add_f32 v[214:215], v[214:215], 1.0 op_sel_hi:[1,0]
	v_cvt_pk_bf16_f32 v132, v208, v209
	v_cvt_pk_bf16_f32 v133, v210, v211
	v_cvt_pk_bf16_f32 v134, v212, v213
	v_cvt_pk_bf16_f32 v135, v214, v215
	v_add_co_u32_e32 v142, vcc, 0x108000, v142
	v_addc_co_u32_e32 v143, vcc, 0, v143, vcc
	global_store_dwordx4 v[142:143], v[132:135], off
	s_or_b32 s9, s8, 0x80
	s_cmpk_gt_i32 s9, 0xaff
	s_mov_b64 s[14:15], -1
	s_cbranch_scc0 .LBB0_433
.LBB0_424:
	s_and_b64 vcc, exec, s[14:15]
	s_cbranch_vccz .LBB0_426
	s_add_i32 s12, s8, 0xffffed80
	s_and_b64 s[8:9], s[10:11], exec
	s_movk_i32 s9, 0x800
	s_cselect_b32 s8, s60, s12
	s_cselect_b32 s10, 0x400, s9
	s_lshl_b32 s26, s10, 1
	s_ashr_i32 s9, s8, 31
	s_lshl_b32 s10, s10, 2
	v_lshl_add_u64 v[132:133], v[140:141], 0, s[26:27]
	s_add_u32 s10, s62, s10
	v_lshl_add_u64 v[160:161], s[8:9], 1, v[132:133]
	s_addc_u32 s11, s63, 0
	s_lshl_b64 s[8:9], s[8:9], 2
	s_add_u32 s8, s10, s8
	s_addc_u32 s9, s11, s9
	v_lshlrev_b32_e32 v0, 1, v155
	v_lshl_add_u64 v[136:137], v[160:161], 0, v[0:1]
	v_pk_fma_f32 v[208:209], v[128:129], v[184:185], v[216:217] op_sel_hi:[1,0,1]
	v_pk_fma_f32 v[210:211], v[130:131], v[184:185], v[218:219] op_sel_hi:[1,0,1]
	v_pk_fma_f32 v[212:213], v[124:125], v[184:185], v[220:221] op_sel_hi:[1,0,1]
	v_pk_fma_f32 v[214:215], v[126:127], v[184:185], v[222:223] op_sel_hi:[1,0,1]
	v_min_f32_e32 v208, 0x42ac0000, v208
	v_min_f32_e32 v209, 0x42ac0000, v209
	v_min_f32_e32 v210, 0x42ac0000, v210
	v_min_f32_e32 v211, 0x42ac0000, v211
	v_min_f32_e32 v212, 0x42ac0000, v212
	v_min_f32_e32 v213, 0x42ac0000, v213
	v_min_f32_e32 v214, 0x42ac0000, v214
	v_min_f32_e32 v215, 0x42ac0000, v215
	v_exp_f32_e32 v208, v208
	v_exp_f32_e32 v209, v209
	v_exp_f32_e32 v210, v210
	v_exp_f32_e32 v211, v211
	v_exp_f32_e32 v212, v212
	v_exp_f32_e32 v213, v213
	v_exp_f32_e32 v214, v214
	v_exp_f32_e32 v215, v215
	v_pk_add_f32 v[208:209], v[208:209], 1.0 op_sel_hi:[1,0]
	v_pk_add_f32 v[210:211], v[210:211], 1.0 op_sel_hi:[1,0]
	v_pk_add_f32 v[212:213], v[212:213], 1.0 op_sel_hi:[1,0]
	v_pk_add_f32 v[214:215], v[214:215], 1.0 op_sel_hi:[1,0]
	v_cvt_pk_bf16_f32 v132, v208, v209
	v_cvt_pk_bf16_f32 v133, v210, v211
	v_cvt_pk_bf16_f32 v134, v212, v213
	v_cvt_pk_bf16_f32 v135, v214, v215
	global_store_dwordx4 v[136:137], v[132:135], off
	v_pk_fma_f32 v[208:209], v[116:117], v[184:185], v[216:217] op_sel:[0,1,0] op_sel_hi:[1,1,1]
	v_pk_fma_f32 v[210:211], v[118:119], v[184:185], v[218:219] op_sel:[0,1,0] op_sel_hi:[1,1,1]
	v_pk_fma_f32 v[212:213], v[108:109], v[184:185], v[220:221] op_sel:[0,1,0] op_sel_hi:[1,1,1]
	v_pk_fma_f32 v[214:215], v[110:111], v[184:185], v[222:223] op_sel:[0,1,0] op_sel_hi:[1,1,1]
	v_min_f32_e32 v208, 0x42ac0000, v208
	v_min_f32_e32 v209, 0x42ac0000, v209
	v_min_f32_e32 v210, 0x42ac0000, v210
	v_min_f32_e32 v211, 0x42ac0000, v211
	v_min_f32_e32 v212, 0x42ac0000, v212
	v_min_f32_e32 v213, 0x42ac0000, v213
	v_min_f32_e32 v214, 0x42ac0000, v214
	v_min_f32_e32 v215, 0x42ac0000, v215
	v_exp_f32_e32 v208, v208
	v_exp_f32_e32 v209, v209
	v_exp_f32_e32 v210, v210
	v_exp_f32_e32 v211, v211
	v_exp_f32_e32 v212, v212
	v_exp_f32_e32 v213, v213
	v_exp_f32_e32 v214, v214
	v_exp_f32_e32 v215, v215
	v_pk_add_f32 v[208:209], v[208:209], 1.0 op_sel_hi:[1,0]
	v_pk_add_f32 v[210:211], v[210:211], 1.0 op_sel_hi:[1,0]
	v_pk_add_f32 v[212:213], v[212:213], 1.0 op_sel_hi:[1,0]
	v_pk_add_f32 v[214:215], v[214:215], 1.0 op_sel_hi:[1,0]
	v_cvt_pk_bf16_f32 v132, v208, v209
	v_cvt_pk_bf16_f32 v133, v210, v211
	v_cvt_pk_bf16_f32 v134, v212, v213
	v_cvt_pk_bf16_f32 v135, v214, v215
	v_add_co_u32_e32 v194, vcc, 0x18000, v136
	v_addc_co_u32_e32 v195, vcc, 0, v137, vcc
	global_store_dwordx4 v[194:195], v[132:135], off
	v_pk_fma_f32 v[208:209], v[92:93], v[186:187], v[216:217] op_sel_hi:[1,0,1]
	v_pk_fma_f32 v[210:211], v[94:95], v[186:187], v[218:219] op_sel_hi:[1,0,1]
	v_pk_fma_f32 v[212:213], v[80:81], v[186:187], v[220:221] op_sel_hi:[1,0,1]
	v_pk_fma_f32 v[214:215], v[82:83], v[186:187], v[222:223] op_sel_hi:[1,0,1]
	v_min_f32_e32 v208, 0x42ac0000, v208
	v_min_f32_e32 v209, 0x42ac0000, v209
; __device__ __forceinline__ u32x4 pack8(const float (&v)[8]) { u32x4 w; w.x = pk2(v[0], v[1]); w.y = pk2(v[2], v[3]); w.z = pk2(v[4], v[5]); w.w = pk2(v[6], v[7]); return w; }
;     __device__ __forceinline__ bool operator()(Acc& acc, const Unit& u, int wr, int wc, int fr, int fq, const LAS float* rstab) const {
;     ...
; #pragma unroll
;                 for (int ai = 0; ai < 2; ++ai)
; #pragma unroll
;                     for (int m = 0; m < 4; ++m) {
;                         const float nrs = -LOG2E * rsp[ai * HALF + m * 16];
;                         float v[8];
; #pragma unroll
;                         for (int e = 0; e < 4; ++e) {
;                             v[e] = 1.0f + __builtin_amdgcn_exp2f(fminf(__builtin_fmaf(acc[ai][bj][m][0][e], nrs, bg[e]), 86.f));
;                             v[4 + e] = 1.0f + __builtin_amdgcn_exp2f(fminf(__builtin_fmaf(acc[ai][bj][m][1][e], nrs, bg[4 + e]), 86.f));
;                         }
;                         gst<u32x4>(p0 + (ai * HALF + m * 16) * 3072, pack8(v));
;                         asm volatile("" ::: "memory");
;                     }
	v_min_f32_e32 v210, 0x42ac0000, v210
	v_min_f32_e32 v211, 0x42ac0000, v211
	v_min_f32_e32 v212, 0x42ac0000, v212
	v_min_f32_e32 v213, 0x42ac0000, v213
	v_min_f32_e32 v214, 0x42ac0000, v214
	v_min_f32_e32 v215, 0x42ac0000, v215
	v_exp_f32_e32 v208, v208
	v_exp_f32_e32 v209, v209
	v_exp_f32_e32 v210, v210
	v_exp_f32_e32 v211, v211
	v_exp_f32_e32 v212, v212
	v_exp_f32_e32 v213, v213
	v_exp_f32_e32 v214, v214
	v_exp_f32_e32 v215, v215
	v_pk_add_f32 v[208:209], v[208:209], 1.0 op_sel_hi:[1,0]
	v_pk_add_f32 v[210:211], v[210:211], 1.0 op_sel_hi:[1,0]
	v_pk_add_f32 v[212:213], v[212:213], 1.0 op_sel_hi:[1,0]
	v_pk_add_f32 v[214:215], v[214:215], 1.0 op_sel_hi:[1,0]
	v_cvt_pk_bf16_f32 v132, v208, v209
	v_cvt_pk_bf16_f32 v133, v210, v211
	v_cvt_pk_bf16_f32 v134, v212, v213
	v_cvt_pk_bf16_f32 v135, v214, v215
	v_add_co_u32_e32 v194, vcc, 0x30000, v136
	v_addc_co_u32_e32 v195, vcc, 0, v137, vcc
	global_store_dwordx4 v[194:195], v[132:135], off
	v_pk_fma_f32 v[208:209], v[64:65], v[186:187], v[216:217] op_sel:[0,1,0] op_sel_hi:[1,1,1]
	v_pk_fma_f32 v[210:211], v[66:67], v[186:187], v[218:219] op_sel:[0,1,0] op_sel_hi:[1,1,1]
	v_pk_fma_f32 v[212:213], v[48:49], v[186:187], v[220:221] op_sel:[0,1,0] op_sel_hi:[1,1,1]
	v_pk_fma_f32 v[214:215], v[50:51], v[186:187], v[222:223] op_sel:[0,1,0] op_sel_hi:[1,1,1]
	v_min_f32_e32 v208, 0x42ac0000, v208
	v_min_f32_e32 v209, 0x42ac0000, v209
	v_min_f32_e32 v210, 0x42ac0000, v210
	v_min_f32_e32 v211, 0x42ac0000, v211
	v_min_f32_e32 v212, 0x42ac0000, v212
	v_min_f32_e32 v213, 0x42ac0000, v213
	v_min_f32_e32 v214, 0x42ac0000, v214
	v_min_f32_e32 v215, 0x42ac0000, v215
	v_exp_f32_e32 v208, v208
	v_exp_f32_e32 v209, v209
	v_exp_f32_e32 v210, v210
	v_exp_f32_e32 v211, v211
	v_exp_f32_e32 v212, v212
	v_exp_f32_e32 v213, v213
	v_exp_f32_e32 v214, v214
	v_exp_f32_e32 v215, v215
	v_pk_add_f32 v[208:209], v[208:209], 1.0 op_sel_hi:[1,0]
	v_pk_add_f32 v[210:211], v[210:211], 1.0 op_sel_hi:[1,0]
	v_pk_add_f32 v[212:213], v[212:213], 1.0 op_sel_hi:[1,0]
	v_pk_add_f32 v[214:215], v[214:215], 1.0 op_sel_hi:[1,0]
	v_cvt_pk_bf16_f32 v132, v208, v209
	v_cvt_pk_bf16_f32 v133, v210, v211
	v_cvt_pk_bf16_f32 v134, v212, v213
	v_cvt_pk_bf16_f32 v135, v214, v215
	v_add_co_u32_e32 v194, vcc, 0x48000, v136
	v_addc_co_u32_e32 v195, vcc, 0, v137, vcc
	global_store_dwordx4 v[194:195], v[132:135], off
	v_pk_fma_f32 v[208:209], v[96:97], v[188:189], v[216:217] op_sel_hi:[1,0,1]
	v_pk_fma_f32 v[210:211], v[98:99], v[188:189], v[218:219] op_sel_hi:[1,0,1]
	v_pk_fma_f32 v[212:213], v[104:105], v[188:189], v[220:221] op_sel_hi:[1,0,1]
	v_pk_fma_f32 v[214:215], v[106:107], v[188:189], v[222:223] op_sel_hi:[1,0,1]
	v_min_f32_e32 v208, 0x42ac0000, v208
	v_min_f32_e32 v209, 0x42ac0000, v209
	v_min_f32_e32 v210, 0x42ac0000, v210
	v_min_f32_e32 v211, 0x42ac0000, v211
	v_min_f32_e32 v212, 0x42ac0000, v212
	v_min_f32_e32 v213, 0x42ac0000, v213
	v_min_f32_e32 v214, 0x42ac0000, v214
	v_min_f32_e32 v215, 0x42ac0000, v215
	v_exp_f32_e32 v208, v208
	v_exp_f32_e32 v209, v209
	v_exp_f32_e32 v210, v210
	v_exp_f32_e32 v211, v211
	v_exp_f32_e32 v212, v212
	v_exp_f32_e32 v213, v213
	v_exp_f32_e32 v214, v214
	v_exp_f32_e32 v215, v215
	v_pk_add_f32 v[208:209], v[208:209], 1.0 op_sel_hi:[1,0]
	v_pk_add_f32 v[210:211], v[210:211], 1.0 op_sel_hi:[1,0]
	v_pk_add_f32 v[212:213], v[212:213], 1.0 op_sel_hi:[1,0]
	v_pk_add_f32 v[214:215], v[214:215], 1.0 op_sel_hi:[1,0]
	v_cvt_pk_bf16_f32 v132, v208, v209
	v_cvt_pk_bf16_f32 v133, v210, v211
	v_cvt_pk_bf16_f32 v134, v212, v213
	v_cvt_pk_bf16_f32 v135, v214, v215
	v_add_co_u32_e32 v194, vcc, 0xc0000, v136
	v_addc_co_u32_e32 v195, vcc, 0, v137, vcc
	global_store_dwordx4 v[194:195], v[132:135], off
	v_pk_fma_f32 v[208:209], v[84:85], v[188:189], v[216:217] op_sel:[0,1,0] op_sel_hi:[1,1,1]
	v_pk_fma_f32 v[210:211], v[86:87], v[188:189], v[218:219] op_sel:[0,1,0] op_sel_hi:[1,1,1]
; __device__ __forceinline__ u32x4 pack8(const float (&v)[8]) { u32x4 w; w.x = pk2(v[0], v[1]); w.y = pk2(v[2], v[3]); w.z = pk2(v[4], v[5]); w.w = pk2(v[6], v[7]); return w; }
;     __device__ __forceinline__ bool operator()(Acc& acc, const Unit& u, int wr, int wc, int fr, int fq, const LAS float* rstab) const {
;     ...
; #pragma unroll
;                 for (int ai = 0; ai < 2; ++ai)
; #pragma unroll
;                     for (int m = 0; m < 4; ++m) {
;                         const float nrs = -LOG2E * rsp[ai * HALF + m * 16];
;                         float v[8];
; #pragma unroll
;                         for (int e = 0; e < 4; ++e) {
;                             v[e] = 1.0f + __builtin_amdgcn_exp2f(fminf(__builtin_fmaf(acc[ai][bj][m][0][e], nrs, bg[e]), 86.f));
;                             v[4 + e] = 1.0f + __builtin_amdgcn_exp2f(fminf(__builtin_fmaf(acc[ai][bj][m][1][e], nrs, bg[4 + e]), 86.f));
;                         }
;                         gst<u32x4>(p0 + (ai * HALF + m * 16) * 3072, pack8(v));
;                         asm volatile("" ::: "memory");
;                     }
	v_pk_fma_f32 v[212:213], v[76:77], v[188:189], v[220:221] op_sel:[0,1,0] op_sel_hi:[1,1,1]
	v_pk_fma_f32 v[214:215], v[78:79], v[188:189], v[222:223] op_sel:[0,1,0] op_sel_hi:[1,1,1]
	v_min_f32_e32 v208, 0x42ac0000, v208
	v_min_f32_e32 v209, 0x42ac0000, v209
	v_min_f32_e32 v210, 0x42ac0000, v210
	v_min_f32_e32 v211, 0x42ac0000, v211
	v_min_f32_e32 v212, 0x42ac0000, v212
	v_min_f32_e32 v213, 0x42ac0000, v213
	v_min_f32_e32 v214, 0x42ac0000, v214
	v_min_f32_e32 v215, 0x42ac0000, v215
	v_exp_f32_e32 v208, v208
	v_exp_f32_e32 v209, v209
	v_exp_f32_e32 v210, v210
	v_exp_f32_e32 v211, v211
	v_exp_f32_e32 v212, v212
	v_exp_f32_e32 v213, v213
	v_exp_f32_e32 v214, v214
	v_exp_f32_e32 v215, v215
	v_pk_add_f32 v[208:209], v[208:209], 1.0 op_sel_hi:[1,0]
	v_pk_add_f32 v[210:211], v[210:211], 1.0 op_sel_hi:[1,0]
	v_pk_add_f32 v[212:213], v[212:213], 1.0 op_sel_hi:[1,0]
	v_pk_add_f32 v[214:215], v[214:215], 1.0 op_sel_hi:[1,0]
	v_cvt_pk_bf16_f32 v132, v208, v209
	v_cvt_pk_bf16_f32 v133, v210, v211
	v_cvt_pk_bf16_f32 v134, v212, v213
	v_cvt_pk_bf16_f32 v135, v214, v215
	v_add_co_u32_e32 v194, vcc, 0xd8000, v136
	v_addc_co_u32_e32 v195, vcc, 0, v137, vcc
	global_store_dwordx4 v[194:195], v[132:135], off
	v_pk_fma_f32 v[208:209], v[52:53], v[190:191], v[216:217] op_sel_hi:[1,0,1]
	v_pk_fma_f32 v[210:211], v[54:55], v[190:191], v[218:219] op_sel_hi:[1,0,1]
	v_pk_fma_f32 v[212:213], v[44:45], v[190:191], v[220:221] op_sel_hi:[1,0,1]
	v_pk_fma_f32 v[214:215], v[46:47], v[190:191], v[222:223] op_sel_hi:[1,0,1]
	v_min_f32_e32 v208, 0x42ac0000, v208
	v_min_f32_e32 v209, 0x42ac0000, v209
	v_min_f32_e32 v210, 0x42ac0000, v210
	v_min_f32_e32 v211, 0x42ac0000, v211
	v_min_f32_e32 v212, 0x42ac0000, v212
	v_min_f32_e32 v213, 0x42ac0000, v213
	v_min_f32_e32 v214, 0x42ac0000, v214
	v_min_f32_e32 v215, 0x42ac0000, v215
	v_exp_f32_e32 v208, v208
	v_exp_f32_e32 v209, v209
	v_exp_f32_e32 v210, v210
	v_exp_f32_e32 v211, v211
	v_exp_f32_e32 v212, v212
	v_exp_f32_e32 v213, v213
	v_exp_f32_e32 v214, v214
	v_exp_f32_e32 v215, v215
	v_pk_add_f32 v[208:209], v[208:209], 1.0 op_sel_hi:[1,0]
	v_pk_add_f32 v[210:211], v[210:211], 1.0 op_sel_hi:[1,0]
	v_pk_add_f32 v[212:213], v[212:213], 1.0 op_sel_hi:[1,0]
	v_pk_add_f32 v[214:215], v[214:215], 1.0 op_sel_hi:[1,0]
	v_cvt_pk_bf16_f32 v132, v208, v209
	v_cvt_pk_bf16_f32 v133, v210, v211
	v_cvt_pk_bf16_f32 v134, v212, v213
	v_cvt_pk_bf16_f32 v135, v214, v215
	v_add_co_u32_e32 v194, vcc, 0xf0000, v136
	v_addc_co_u32_e32 v195, vcc, 0, v137, vcc
	global_store_dwordx4 v[194:195], v[132:135], off
	v_pk_fma_f32 v[208:209], v[24:25], v[190:191], v[216:217] op_sel:[0,1,0] op_sel_hi:[1,1,1]
	v_pk_fma_f32 v[210:211], v[26:27], v[190:191], v[218:219] op_sel:[0,1,0] op_sel_hi:[1,1,1]
	v_pk_fma_f32 v[212:213], v[20:21], v[190:191], v[220:221] op_sel:[0,1,0] op_sel_hi:[1,1,1]
	v_pk_fma_f32 v[214:215], v[22:23], v[190:191], v[222:223] op_sel:[0,1,0] op_sel_hi:[1,1,1]
	v_min_f32_e32 v208, 0x42ac0000, v208
	v_min_f32_e32 v209, 0x42ac0000, v209
	v_min_f32_e32 v210, 0x42ac0000, v210
	v_min_f32_e32 v211, 0x42ac0000, v211
	v_min_f32_e32 v212, 0x42ac0000, v212
	v_min_f32_e32 v213, 0x42ac0000, v213
	v_min_f32_e32 v214, 0x42ac0000, v214
	v_min_f32_e32 v215, 0x42ac0000, v215
	v_exp_f32_e32 v208, v208
	v_exp_f32_e32 v209, v209
	v_exp_f32_e32 v210, v210
	v_exp_f32_e32 v211, v211
	v_exp_f32_e32 v212, v212
	v_exp_f32_e32 v213, v213
	v_exp_f32_e32 v214, v214
	v_exp_f32_e32 v215, v215
	v_pk_add_f32 v[208:209], v[208:209], 1.0 op_sel_hi:[1,0]
	v_pk_add_f32 v[210:211], v[210:211], 1.0 op_sel_hi:[1,0]
	v_pk_add_f32 v[212:213], v[212:213], 1.0 op_sel_hi:[1,0]
	v_pk_add_f32 v[214:215], v[214:215], 1.0 op_sel_hi:[1,0]
	v_cvt_pk_bf16_f32 v132, v208, v209
	v_cvt_pk_bf16_f32 v133, v210, v211
	v_cvt_pk_bf16_f32 v134, v212, v213
	v_cvt_pk_bf16_f32 v135, v214, v215
	v_add_co_u32_e32 v136, vcc, 0x108000, v136
	v_addc_co_u32_e32 v137, vcc, 0, v137, vcc
	global_store_dwordx4 v[136:137], v[132:135], off
